# S5 forward scan: per-step complex multiply-add rewritten from 5 dependent packed-f32 ops + hazard nops to a 3-deep chain of plain f32 mul/fma/add with identical rounding
# speedup vs baseline: 1.0105x; 1.0030x over previous
; __device__ __forceinline__ bf16_t f2bf(float f) { unsigned u = __float_as_uint(f); return (bf16_t)((u + 0x7fffu + ((u >> 16) & 1u)) >> 16); }
; #define S5_STEP(r) do { const float sr = sl[(r) * 256], si = sl[(r) * 256 + 64]; const float nr = lr * xr - li * xi + sr, ni = lr * xi + li * xr + si; xr = nr; xi = ni; } while (0)
; __device__ __forceinline__ void ph_s5_out(unsigned char* lds_, const bf16_t* Z, const bf16_t* TZB, const bf16_t* CQ, const float2* LP, const float* SLOC, const float* lamT, bf16_t* YG, int nrct, int u0, int ustep) { PH_IDS;
;     ...
;             if (lat) {
;                 if (d == 0) { for (int r = 0; r < 4 + c0; ++r) S5_STEP(r);
;                     for (int r = 0; r < 16; ++r) { xp[r * 256] = f2bf(xr); xp[r * 256 + 64] = f2bf(xi); S5_STEP(4 + c0 + r); } }
;                 else { for (int r = 3; r >= 0; --r) S5_STEP(r);
;                     for (int c = 31; c >= c0 + 16; --c) S5_STEP(4 + c);
;                     for (int r = 15; r >= 0; --r) { xp[r * 256] = f2bf(xr); xp[r * 256 + 64] = f2bf(xi); S5_STEP(4 + c0 + r); } }
.LBB0_866:
	ds_read2st64_b32 v[22:23], v19 offset1:1
	ds_read2st64_b32 v[24:25], v19 offset0:4 offset1:5
	ds_read2st64_b32 v[26:27], v19 offset0:8 offset1:9
	ds_read2st64_b32 v[28:29], v19 offset0:12 offset1:13
	ds_read2st64_b32 v[30:31], v19 offset0:16 offset1:17
	ds_read2st64_b32 v[32:33], v19 offset0:20 offset1:21
	ds_read2st64_b32 v[34:35], v19 offset0:24 offset1:25
	ds_read2st64_b32 v[36:37], v19 offset0:28 offset1:29
	s_add_i32 s14, s14, 8
	v_add_u32_e32 v19, 0x2000, v19
	v_mul_f32_e32 v20, v8, v12
	v_mul_f32_e32 v21, v9, v12
	v_fma_f32 v20, v6, v10, -v20
	v_fma_f32 v21, v7, v10, v21
	s_waitcnt lgkmcnt(7)
	v_add_f32_e32 v10, v20, v22
	v_add_f32_e32 v11, v21, v23
	v_mul_f32_e32 v20, v8, v11
	v_mul_f32_e32 v21, v9, v11
	v_fma_f32 v20, v6, v10, -v20
	v_fma_f32 v21, v7, v10, v21
	s_waitcnt lgkmcnt(6)
	v_add_f32_e32 v10, v20, v24
	v_add_f32_e32 v11, v21, v25
	v_mul_f32_e32 v20, v8, v11
	v_mul_f32_e32 v21, v9, v11
	v_fma_f32 v20, v6, v10, -v20
	v_fma_f32 v21, v7, v10, v21
	s_waitcnt lgkmcnt(5)
	v_add_f32_e32 v10, v20, v26
	v_add_f32_e32 v11, v21, v27
	v_mul_f32_e32 v20, v8, v11
	v_mul_f32_e32 v21, v9, v11
	v_fma_f32 v20, v6, v10, -v20
	v_fma_f32 v21, v7, v10, v21
	s_waitcnt lgkmcnt(4)
	v_add_f32_e32 v10, v20, v28
	v_add_f32_e32 v11, v21, v29
	v_mul_f32_e32 v20, v8, v11
	v_mul_f32_e32 v21, v9, v11
	v_fma_f32 v20, v6, v10, -v20
	v_fma_f32 v21, v7, v10, v21
	s_waitcnt lgkmcnt(3)
	v_add_f32_e32 v10, v20, v30
	v_add_f32_e32 v11, v21, v31
	v_mul_f32_e32 v20, v8, v11
	v_mul_f32_e32 v21, v9, v11
	v_fma_f32 v20, v6, v10, -v20
	v_fma_f32 v21, v7, v10, v21
	s_waitcnt lgkmcnt(2)
	v_add_f32_e32 v10, v20, v32
	v_add_f32_e32 v11, v21, v33
	v_mul_f32_e32 v20, v8, v11
	v_mul_f32_e32 v21, v9, v11
	v_fma_f32 v20, v6, v10, -v20
	v_fma_f32 v21, v7, v10, v21
	s_waitcnt lgkmcnt(1)
	v_add_f32_e32 v10, v20, v34
	v_add_f32_e32 v11, v21, v35
	v_mul_f32_e32 v20, v8, v11
	v_mul_f32_e32 v21, v9, v11
	v_fma_f32 v20, v6, v10, -v20
	v_fma_f32 v21, v7, v10, v21
	s_waitcnt lgkmcnt(0)
	v_add_f32_e32 v10, v20, v36
	v_add_f32_e32 v11, v21, v37
	s_cmp_lg_u32 s17, s14
	v_mov_b32_e32 v12, v11
	s_cbranch_scc1 .LBB0_866
	s_mov_b64 s[14:15], 0
